# v95 plus one static s_setprio 1 for waves 0-3 (mirror of the previous try) across the P5 work-queue phase, reset to 0 before the P5->P6 sync
# speedup vs baseline: 1.0031x; 1.0031x over previous
.LBB0_316:
	s_or_b64 exec, exec, s[4:5]
	v_readfirstlane_b32 s0, v254
	s_nop 3
	s_lshr_b32 s0, s0, 6
	s_cmp_ge_u32 s0, 4
	s_cbranch_scc1 .Lp5prio_done
	s_setprio 1
